# hot-loop entry alignment: GEMM K-loop and attention step loop headers padded to 64-byte boundaries
# baseline (speedup 1.0000x reference)
; #define PG8_STAGE(bufoff, gbase, voff) do { _Pragma("unroll") for (int _i = 0; _i < 2; ++_i) \
;         __builtin_amdgcn_global_load_lds((const unsigned*)((const char*)(gbase) + (voff)[_i]), (LAS unsigned*)(lds + (bufoff) + ldsw + _i * 8192), 16, 0, 0); } while (0)
; #define PG8_LDA(dst, b, h) do { _Pragma("unroll") for (int m = 0; m < 4; ++m) _Pragma("unroll") for (int k = 0; k < 2; ++k) dst[m][k] = *(const LAS bf16x8*)(lds + PG8_SA(b, h) + aoff + m * 2048 + k * 1024); } while (0)
; #define PG8_LDB(dst, b, h) do { _Pragma("unroll") for (int n = 0; n < 2; ++n) _Pragma("unroll") for (int k = 0; k < 2; ++k) dst[n][k] = *(const LAS bf16x8*)(lds + PG8_SB(b, h) + boff + n * 2048 + k * 1024); } while (0)
; #define PG8_MMA(ai, bj, At, Bt) do { __builtin_amdgcn_s_setprio(1); _Pragma("unroll") for (int m = 0; m < 4; ++m) _Pragma("unroll") for (int n = 0; n < 2; ++n) _Pragma("unroll") for (int k = 0; k < 2; ++k) \
;         acc[ai][bj][m][n] = __builtin_amdgcn_mfma_f32_16x16x32_bf16(Bt[n][k], At[m][k], acc[ai][bj][m][n], 0, 0, 0); __builtin_amdgcn_s_setprio(0); } while (0)
; #define PG8_BAR __builtin_amdgcn_s_barrier()
; template <class Epi, class Sched>
; __device__ __forceinline__ void gemm_phase(LAS unsigned char* lds, const Sched& S, const Epi& E, bool natural = false) {
;     ...
;         const bool has_next = S.next(ui + 1, nxt);
;         const char* nA = cA; const char* nB = cB; if (has_next) S.ptrs(nxt, nA, nB);
;         for (int t = 0; t < nt; t += 2) {
;             const bool last = (t == nt - 2);
;             const char* a1 = cA + (size_t)(t + 1) * kstep;
;             const char* a2 = last ? nA : cA + (size_t)(t + 2) * kstep; const char* b2 = last ? nB : cB + (size_t)(t + 2) * kstep;
;             const char* a3 = a2 + kstep; const char* b3 = b2 + kstep;
;             if constexpr (Epi::MIDHOOK) { if (t == nt / 2) E.mid(acc, cur, wr, wc, fr, fq); }
;             PG8_LDB(B0, 0, 0); PG8_LDB(B1, 0, 1); PG8_SCHED; PG8_LDA(At, 0, 0); PG8_STAGE(PG8_SA(1, 1), a1 + hstep, voffA);
;             PG8_WAIT_V(8); PG8_WAIT_L(0); PG8_BAR; PG8_MMA(0, 0, At, B0); PG8_MMA(0, 1, At, B1); PG8_BAR; PG8_SCHED;
;             PG8_LDA(At, 0, 1); PG8_STAGE(PG8_SB(0, 0), b2, voffB0); PG8_STAGE(PG8_SB(0, 1), b2, voffB1); PG8_STAGE(PG8_SA(0, 0), a2, voffA);
;             PG8_WAIT_V(8); PG8_WAIT_L(0); PG8_BAR; PG8_MMA(1, 0, At, B0); PG8_MMA(1, 1, At, B1); PG8_BAR; PG8_SCHED;
.LBB0_173:
	s_add_u32 s40, s40, 0x40080
	s_addc_u32 s41, s41, 0
	s_add_u32 s31, s42, 0x100
	s_addc_u32 s35, s43, 0
	s_mov_b32 s71, -2
	ds_read_b128 v[128:131], v196
	ds_read_b128 v[132:135], v196 offset:1024
	ds_read_b128 v[136:139], v196 offset:2048
	ds_read_b128 v[140:143], v196 offset:3072
	ds_read_b128 v[144:147], v197
	ds_read_b128 v[148:151], v197 offset:1024
	ds_read_b128 v[186:189], v197 offset:2048
	ds_read_b128 v[202:205], v197 offset:3072
	s_add_u32 s42, s40, 0xfffc0080
	s_addc_u32 s43, s41, -1
	s_cmp_eq_u32 s71, 12
	s_cselect_b32 s45, s1, s43
	s_cselect_b32 s44, s0, s42
	s_cselect_b32 s43, s37, s35
	s_cselect_b32 s42, s36, s31
	v_lshl_add_u64 v[238:239], s[40:41], 0, v[178:179]
	s_add_i32 m0, s39, 0xc000
	ds_read_b128 v[206:209], v198
	ds_read_b128 v[210:213], v198 offset:1024
	ds_read_b128 v[214:217], v198 offset:2048
	ds_read_b128 v[218:221], v198 offset:3072
	ds_read_b128 v[222:225], v198 offset:4096
	ds_read_b128 v[226:229], v198 offset:5120
	ds_read_b128 v[230:233], v198 offset:6144
	ds_read_b128 v[234:237], v198 offset:7168
	global_load_lds_dwordx4 v[238:239], off
	v_lshl_add_u64 v[238:239], s[40:41], 0, v[180:181]
	s_add_i32 m0, s39, 0xe000
	s_nop 0
	global_load_lds_dwordx4 v[238:239], off
	s_waitcnt vmcnt(8)
	s_waitcnt lgkmcnt(0)
	s_barrier
	s_setprio 1
	s_waitcnt lgkmcnt(0)
	v_mfma_f32_16x16x32_bf16 v[124:127], v[128:131], v[206:209], 0
	v_mfma_f32_16x16x32_bf16 v[120:123], v[136:139], v[206:209], 0
	v_mfma_f32_16x16x32_bf16 v[108:111], v[128:131], v[214:217], 0
	v_mfma_f32_16x16x32_bf16 v[104:107], v[136:139], v[214:217], 0
	v_mfma_f32_16x16x32_bf16 v[92:95], v[128:131], v[222:225], 0
	v_mfma_f32_16x16x32_bf16 v[88:91], v[136:139], v[222:225], 0
	v_mfma_f32_16x16x32_bf16 v[76:79], v[128:131], v[230:233], 0
	v_mfma_f32_16x16x32_bf16 v[72:75], v[136:139], v[230:233], 0
	v_mfma_f32_16x16x32_bf16 v[124:127], v[132:135], v[210:213], v[124:127]
	v_mfma_f32_16x16x32_bf16 v[120:123], v[140:143], v[210:213], v[120:123]
	v_mfma_f32_16x16x32_bf16 v[108:111], v[132:135], v[218:221], v[108:111]
	v_mfma_f32_16x16x32_bf16 v[104:107], v[140:143], v[218:221], v[104:107]
	v_mfma_f32_16x16x32_bf16 v[92:95], v[132:135], v[226:229], v[92:95]
	v_mfma_f32_16x16x32_bf16 v[88:91], v[140:143], v[226:229], v[88:91]
	v_mfma_f32_16x16x32_bf16 v[76:79], v[132:135], v[234:237], v[76:79]
	v_mfma_f32_16x16x32_bf16 v[72:75], v[140:143], v[234:237], v[72:75]
	s_setprio 0
	s_setprio 1
	v_mfma_f32_16x16x32_bf16 v[116:119], v[144:147], v[206:209], 0
	v_mfma_f32_16x16x32_bf16 v[112:115], v[186:189], v[206:209], 0
	v_mfma_f32_16x16x32_bf16 v[100:103], v[144:147], v[214:217], 0
	v_mfma_f32_16x16x32_bf16 v[96:99], v[186:189], v[214:217], 0
	v_mfma_f32_16x16x32_bf16 v[84:87], v[144:147], v[222:225], 0
	v_mfma_f32_16x16x32_bf16 v[80:83], v[186:189], v[222:225], 0
	v_mfma_f32_16x16x32_bf16 v[68:71], v[144:147], v[230:233], 0
	v_mfma_f32_16x16x32_bf16 v[64:67], v[186:189], v[230:233], 0
	v_mfma_f32_16x16x32_bf16 v[116:119], v[148:151], v[210:213], v[116:119]
	v_mfma_f32_16x16x32_bf16 v[112:115], v[202:205], v[210:213], v[112:115]
	v_mfma_f32_16x16x32_bf16 v[100:103], v[148:151], v[218:221], v[100:103]
	v_mfma_f32_16x16x32_bf16 v[96:99], v[202:205], v[218:221], v[96:99]
	v_mfma_f32_16x16x32_bf16 v[84:87], v[148:151], v[226:229], v[84:87]
	v_mfma_f32_16x16x32_bf16 v[80:83], v[202:205], v[226:229], v[80:83]
	v_mfma_f32_16x16x32_bf16 v[68:71], v[148:151], v[234:237], v[68:71]
	v_mfma_f32_16x16x32_bf16 v[64:67], v[202:205], v[234:237], v[64:67]
	s_setprio 0
	s_barrier
	s_add_i32 s72, s59, s33
	v_lshl_add_u64 v[238:239], s[42:43], 0, v[156:157]
	s_mov_b32 m0, s72
	ds_read_b128 v[206:209], v198 offset:16384
	ds_read_b128 v[210:213], v198 offset:17408
	ds_read_b128 v[214:217], v198 offset:18432
	ds_read_b128 v[218:221], v198 offset:19456
	ds_read_b128 v[222:225], v198 offset:20480
	ds_read_b128 v[226:229], v198 offset:21504
	ds_read_b128 v[230:233], v198 offset:22528
	ds_read_b128 v[234:237], v198 offset:23552
	global_load_lds_dwordx4 v[238:239], off
	v_lshl_add_u64 v[240:241], s[42:43], 0, v[162:163]
	s_add_i32 m0, s72, 0x2000
	s_add_i32 s72, s60, s33
	global_load_lds_dwordx4 v[240:241], off
	v_lshl_add_u64 v[242:243], s[42:43], 0, v[158:159]
	s_mov_b32 m0, s72
	v_lshl_add_u64 v[244:245], s[44:45], 0, v[160:161]
	global_load_lds_dwordx4 v[242:243], off
	v_lshl_add_u64 v[242:243], s[42:43], 0, v[164:165]
	s_add_i32 m0, s72, 0x2000
	s_nop 0
	global_load_lds_dwordx4 v[242:243], off
	v_lshl_add_u64 v[242:243], s[44:45], 0, v[154:155]
	s_mov_b32 m0, s39
	s_nop 0
	global_load_lds_dwordx4 v[242:243], off
	s_mov_b32 m0, s46
	s_nop 0
	global_load_lds_dwordx4 v[244:245], off
	s_waitcnt vmcnt(8)
	s_waitcnt lgkmcnt(0)
	s_barrier
; #define PG8_STAGE(bufoff, gbase, voff) do { _Pragma("unroll") for (int _i = 0; _i < 2; ++_i) \
;         __builtin_amdgcn_global_load_lds((const unsigned*)((const char*)(gbase) + (voff)[_i]), (LAS unsigned*)(lds + (bufoff) + ldsw + _i * 8192), 16, 0, 0); } while (0)
; #define PG8_LDA(dst, b, h) do { _Pragma("unroll") for (int m = 0; m < 4; ++m) _Pragma("unroll") for (int k = 0; k < 2; ++k) dst[m][k] = *(const LAS bf16x8*)(lds + PG8_SA(b, h) + aoff + m * 2048 + k * 1024); } while (0)
; #define PG8_LDB(dst, b, h) do { _Pragma("unroll") for (int n = 0; n < 2; ++n) _Pragma("unroll") for (int k = 0; k < 2; ++k) dst[n][k] = *(const LAS bf16x8*)(lds + PG8_SB(b, h) + boff + n * 2048 + k * 1024); } while (0)
; #define PG8_MMA(ai, bj, At, Bt) do { __builtin_amdgcn_s_setprio(1); _Pragma("unroll") for (int m = 0; m < 4; ++m) _Pragma("unroll") for (int n = 0; n < 2; ++n) _Pragma("unroll") for (int k = 0; k < 2; ++k) \
;         acc[ai][bj][m][n] = __builtin_amdgcn_mfma_f32_16x16x32_bf16(Bt[n][k], At[m][k], acc[ai][bj][m][n], 0, 0, 0); __builtin_amdgcn_s_setprio(0); } while (0)
; #define PG8_WAIT_V(n) asm volatile("s_waitcnt vmcnt(" #n ")" ::: "memory")
; #define PG8_WAIT_L(n) asm volatile("s_waitcnt lgkmcnt(" #n ")" ::: "memory")
; #define PG8_BAR __builtin_amdgcn_s_barrier()
; #define PG8_SCHED __builtin_amdgcn_sched_barrier(0)
; template <class Epi, class Sched>
; __device__ __forceinline__ void gemm_phase(LAS unsigned char* lds, const Sched& S, const Epi& E, bool natural = false) {
;     ...
;             PG8_WAIT_V(8); PG8_WAIT_L(0); PG8_BAR; PG8_MMA(1, 0, At, B0); PG8_MMA(1, 1, At, B1); PG8_BAR; PG8_SCHED;
;             PG8_LDB(B0, 1, 0); PG8_LDB(B1, 1, 1); PG8_SCHED; PG8_LDA(At, 1, 0); PG8_STAGE(PG8_SA(0, 1), a2 + hstep, voffA);
;             PG8_WAIT_V(8); PG8_WAIT_L(0); PG8_BAR; PG8_MMA(0, 0, At, B0); PG8_MMA(0, 1, At, B1); PG8_BAR; PG8_SCHED;
	s_setprio 1
	s_waitcnt lgkmcnt(0)
	v_mfma_f32_16x16x32_bf16 v[60:63], v[128:131], v[206:209], 0
	v_mfma_f32_16x16x32_bf16 v[56:59], v[136:139], v[206:209], 0
	v_mfma_f32_16x16x32_bf16 v[44:47], v[128:131], v[214:217], 0
	v_mfma_f32_16x16x32_bf16 v[40:43], v[136:139], v[214:217], 0
	v_mfma_f32_16x16x32_bf16 v[28:31], v[128:131], v[222:225], 0
	v_mfma_f32_16x16x32_bf16 v[24:27], v[136:139], v[222:225], 0
	v_mfma_f32_16x16x32_bf16 v[12:15], v[128:131], v[230:233], 0
	v_mfma_f32_16x16x32_bf16 v[8:11], v[136:139], v[230:233], 0
	v_mfma_f32_16x16x32_bf16 v[60:63], v[132:135], v[210:213], v[60:63]
	v_mfma_f32_16x16x32_bf16 v[56:59], v[140:143], v[210:213], v[56:59]
	v_mfma_f32_16x16x32_bf16 v[44:47], v[132:135], v[218:221], v[44:47]
	v_mfma_f32_16x16x32_bf16 v[40:43], v[140:143], v[218:221], v[40:43]
	v_mfma_f32_16x16x32_bf16 v[28:31], v[132:135], v[226:229], v[28:31]
	v_mfma_f32_16x16x32_bf16 v[24:27], v[140:143], v[226:229], v[24:27]
	v_mfma_f32_16x16x32_bf16 v[12:15], v[132:135], v[234:237], v[12:15]
	v_mfma_f32_16x16x32_bf16 v[8:11], v[140:143], v[234:237], v[8:11]
	s_setprio 0
	s_setprio 1
	v_mfma_f32_16x16x32_bf16 v[52:55], v[144:147], v[206:209], 0
	v_mfma_f32_16x16x32_bf16 v[48:51], v[186:189], v[206:209], 0
	v_mfma_f32_16x16x32_bf16 v[36:39], v[144:147], v[214:217], 0
	v_mfma_f32_16x16x32_bf16 v[32:35], v[186:189], v[214:217], 0
	v_mfma_f32_16x16x32_bf16 v[20:23], v[144:147], v[222:225], 0
	v_mfma_f32_16x16x32_bf16 v[16:19], v[186:189], v[222:225], 0
	v_mfma_f32_16x16x32_bf16 v[4:7], v[144:147], v[230:233], 0
	v_mfma_f32_16x16x32_bf16 v[0:3], v[186:189], v[230:233], 0
	v_mfma_f32_16x16x32_bf16 v[52:55], v[148:151], v[210:213], v[52:55]
	v_mfma_f32_16x16x32_bf16 v[48:51], v[202:205], v[210:213], v[48:51]
	v_mfma_f32_16x16x32_bf16 v[36:39], v[148:151], v[218:221], v[36:39]
	v_mfma_f32_16x16x32_bf16 v[32:35], v[202:205], v[218:221], v[32:35]
	v_mfma_f32_16x16x32_bf16 v[20:23], v[148:151], v[226:229], v[20:23]
	v_mfma_f32_16x16x32_bf16 v[16:19], v[202:205], v[226:229], v[16:19]
	v_mfma_f32_16x16x32_bf16 v[4:7], v[148:151], v[234:237], v[4:7]
	v_mfma_f32_16x16x32_bf16 v[0:3], v[202:205], v[234:237], v[0:3]
	s_setprio 0
	s_barrier
	s_add_i32 s72, 0, 0x18000
	s_add_i32 s73, 0, 0x1c000
	v_add_u32_e32 v140, s72, v192
	v_add_u32_e32 v166, s73, v192
	ds_read_b128 v[128:131], v140
	ds_read_b128 v[132:135], v140 offset:1024
	ds_read_b128 v[136:139], v140 offset:2048
	ds_read_b128 v[140:143], v140 offset:3072
	ds_read_b128 v[144:147], v166
	ds_read_b128 v[148:151], v166 offset:1024
	ds_read_b128 v[186:189], v166 offset:2048
	ds_read_b128 v[202:205], v166 offset:3072
	s_add_u32 s44, s44, 0x40000
	s_addc_u32 s45, s45, 0
	s_mov_b32 m0, s47
	v_lshl_add_u64 v[246:247], s[44:45], 0, v[154:155]
	ds_read_b128 v[206:209], v198 offset:32768
	ds_read_b128 v[210:213], v198 offset:33792
	ds_read_b128 v[214:217], v198 offset:34816
	ds_read_b128 v[218:221], v198 offset:35840
	ds_read_b128 v[222:225], v198 offset:36864
	ds_read_b128 v[226:229], v198 offset:37888
	ds_read_b128 v[230:233], v198 offset:38912
	ds_read_b128 v[234:237], v198 offset:39936
	global_load_lds_dwordx4 v[246:247], off
	v_lshl_add_u64 v[246:247], s[44:45], 0, v[160:161]
	s_mov_b32 m0, s49
	s_nop 0
	global_load_lds_dwordx4 v[246:247], off
	s_waitcnt vmcnt(8)
	s_waitcnt lgkmcnt(0)
	s_barrier
	s_setprio 1
	s_waitcnt lgkmcnt(0)
	v_mfma_f32_16x16x32_bf16 v[124:127], v[128:131], v[206:209], v[124:127]
	v_mfma_f32_16x16x32_bf16 v[120:123], v[136:139], v[206:209], v[120:123]
	v_mfma_f32_16x16x32_bf16 v[108:111], v[128:131], v[214:217], v[108:111]
	v_mfma_f32_16x16x32_bf16 v[104:107], v[136:139], v[214:217], v[104:107]
	v_mfma_f32_16x16x32_bf16 v[92:95], v[128:131], v[222:225], v[92:95]
	v_mfma_f32_16x16x32_bf16 v[88:91], v[136:139], v[222:225], v[88:91]
	v_mfma_f32_16x16x32_bf16 v[76:79], v[128:131], v[230:233], v[76:79]
	v_mfma_f32_16x16x32_bf16 v[72:75], v[136:139], v[230:233], v[72:75]
	v_mfma_f32_16x16x32_bf16 v[124:127], v[132:135], v[210:213], v[124:127]
	v_mfma_f32_16x16x32_bf16 v[120:123], v[140:143], v[210:213], v[120:123]
	v_mfma_f32_16x16x32_bf16 v[108:111], v[132:135], v[218:221], v[108:111]
	v_mfma_f32_16x16x32_bf16 v[104:107], v[140:143], v[218:221], v[104:107]
	v_mfma_f32_16x16x32_bf16 v[92:95], v[132:135], v[226:229], v[92:95]
	v_mfma_f32_16x16x32_bf16 v[88:91], v[140:143], v[226:229], v[88:91]
	v_mfma_f32_16x16x32_bf16 v[76:79], v[132:135], v[234:237], v[76:79]
	v_mfma_f32_16x16x32_bf16 v[72:75], v[140:143], v[234:237], v[72:75]
	s_setprio 0
	s_setprio 1
	v_mfma_f32_16x16x32_bf16 v[116:119], v[144:147], v[206:209], v[116:119]
	v_mfma_f32_16x16x32_bf16 v[112:115], v[186:189], v[206:209], v[112:115]
	v_mfma_f32_16x16x32_bf16 v[100:103], v[144:147], v[214:217], v[100:103]
	v_mfma_f32_16x16x32_bf16 v[96:99], v[186:189], v[214:217], v[96:99]
	v_mfma_f32_16x16x32_bf16 v[84:87], v[144:147], v[222:225], v[84:87]
	v_mfma_f32_16x16x32_bf16 v[80:83], v[186:189], v[222:225], v[80:83]
	v_mfma_f32_16x16x32_bf16 v[68:71], v[144:147], v[230:233], v[68:71]
	v_mfma_f32_16x16x32_bf16 v[64:67], v[186:189], v[230:233], v[64:67]
	v_mfma_f32_16x16x32_bf16 v[116:119], v[148:151], v[210:213], v[116:119]
	v_mfma_f32_16x16x32_bf16 v[112:115], v[202:205], v[210:213], v[112:115]
	v_mfma_f32_16x16x32_bf16 v[100:103], v[148:151], v[218:221], v[100:103]
	v_mfma_f32_16x16x32_bf16 v[96:99], v[202:205], v[218:221], v[96:99]
	v_mfma_f32_16x16x32_bf16 v[84:87], v[148:151], v[226:229], v[84:87]
	v_mfma_f32_16x16x32_bf16 v[80:83], v[202:205], v[226:229], v[80:83]
	v_mfma_f32_16x16x32_bf16 v[68:71], v[148:151], v[234:237], v[68:71]
	v_mfma_f32_16x16x32_bf16 v[64:67], v[202:205], v[234:237], v[64:67]
	s_setprio 0
	s_barrier
; #define PG8_STAGE(bufoff, gbase, voff) do { _Pragma("unroll") for (int _i = 0; _i < 2; ++_i) \
;         __builtin_amdgcn_global_load_lds((const unsigned*)((const char*)(gbase) + (voff)[_i]), (LAS unsigned*)(lds + (bufoff) + ldsw + _i * 8192), 16, 0, 0); } while (0)
; #define PG8_LDA(dst, b, h) do { _Pragma("unroll") for (int m = 0; m < 4; ++m) _Pragma("unroll") for (int k = 0; k < 2; ++k) dst[m][k] = *(const LAS bf16x8*)(lds + PG8_SA(b, h) + aoff + m * 2048 + k * 1024); } while (0)
; #define PG8_MMA(ai, bj, At, Bt) do { __builtin_amdgcn_s_setprio(1); _Pragma("unroll") for (int m = 0; m < 4; ++m) _Pragma("unroll") for (int n = 0; n < 2; ++n) _Pragma("unroll") for (int k = 0; k < 2; ++k) \
;         acc[ai][bj][m][n] = __builtin_amdgcn_mfma_f32_16x16x32_bf16(Bt[n][k], At[m][k], acc[ai][bj][m][n], 0, 0, 0); __builtin_amdgcn_s_setprio(0); } while (0)
; #define PG8_WAIT_V(n) asm volatile("s_waitcnt vmcnt(" #n ")" ::: "memory")
; #define PG8_WAIT_L(n) asm volatile("s_waitcnt lgkmcnt(" #n ")" ::: "memory")
; #define PG8_BAR __builtin_amdgcn_s_barrier()
; #define PG8_SCHED __builtin_amdgcn_sched_barrier(0)
; template <class Epi, class Sched>
; __device__ __forceinline__ void gemm_phase(LAS unsigned char* lds, const Sched& S, const Epi& E, bool natural = false) {
;     ...
;             PG8_LDA(At, 1, 1); PG8_STAGE(PG8_SB(1, 0), b3, voffB0); PG8_STAGE(PG8_SB(1, 1), b3, voffB1); PG8_STAGE(PG8_SA(1, 0), a3, voffA);
;             PG8_WAIT_V(8); PG8_WAIT_L(0); PG8_BAR; PG8_MMA(1, 0, At, B0); PG8_MMA(1, 1, At, B1); PG8_BAR; PG8_SCHED;
;         }
	s_add_u32 s42, s42, 0x80
	s_addc_u32 s43, s43, 0
	s_add_i32 s44, s72, s33
	v_lshl_add_u64 v[238:239], v[238:239], 0, s[12:13]
	s_mov_b32 m0, s44
	ds_read_b128 v[206:209], v198 offset:49152
	ds_read_b128 v[210:213], v198 offset:50176
	ds_read_b128 v[214:217], v198 offset:51200
	ds_read_b128 v[218:221], v198 offset:52224
	ds_read_b128 v[222:225], v198 offset:53248
	ds_read_b128 v[226:229], v198 offset:54272
	ds_read_b128 v[230:233], v198 offset:55296
	ds_read_b128 v[234:237], v198 offset:56320
	global_load_lds_dwordx4 v[238:239], off
	v_lshl_add_u64 v[238:239], v[240:241], 0, s[12:13]
	s_add_i32 m0, s44, 0x2000
	s_add_i32 s44, s73, s33
	global_load_lds_dwordx4 v[238:239], off
	v_lshl_add_u64 v[238:239], s[42:43], 0, v[158:159]
	s_mov_b32 m0, s44
	s_nop 0
	global_load_lds_dwordx4 v[238:239], off
	v_lshl_add_u64 v[238:239], s[42:43], 0, v[164:165]
	s_add_i32 m0, s44, 0x2000
	s_nop 0
	global_load_lds_dwordx4 v[238:239], off
	v_lshl_add_u64 v[238:239], v[242:243], 0, s[12:13]
	s_mov_b32 m0, s51
	s_nop 0
	global_load_lds_dwordx4 v[238:239], off
	v_lshl_add_u64 v[238:239], v[244:245], 0, s[12:13]
	s_mov_b32 m0, s52
	s_nop 0
	global_load_lds_dwordx4 v[238:239], off
	s_waitcnt vmcnt(8)
	s_waitcnt lgkmcnt(0)
	s_barrier
	s_setprio 1
	s_waitcnt lgkmcnt(0)
	v_mfma_f32_16x16x32_bf16 v[60:63], v[128:131], v[206:209], v[60:63]
	v_mfma_f32_16x16x32_bf16 v[56:59], v[136:139], v[206:209], v[56:59]
	v_mfma_f32_16x16x32_bf16 v[44:47], v[128:131], v[214:217], v[44:47]
	v_mfma_f32_16x16x32_bf16 v[40:43], v[136:139], v[214:217], v[40:43]
	v_mfma_f32_16x16x32_bf16 v[28:31], v[128:131], v[222:225], v[28:31]
	v_mfma_f32_16x16x32_bf16 v[24:27], v[136:139], v[222:225], v[24:27]
	v_mfma_f32_16x16x32_bf16 v[12:15], v[128:131], v[230:233], v[12:15]
	v_mfma_f32_16x16x32_bf16 v[8:11], v[136:139], v[230:233], v[8:11]
	v_mfma_f32_16x16x32_bf16 v[60:63], v[132:135], v[210:213], v[60:63]
	v_mfma_f32_16x16x32_bf16 v[56:59], v[140:143], v[210:213], v[56:59]
	v_mfma_f32_16x16x32_bf16 v[44:47], v[132:135], v[218:221], v[44:47]
	v_mfma_f32_16x16x32_bf16 v[40:43], v[140:143], v[218:221], v[40:43]
	v_mfma_f32_16x16x32_bf16 v[28:31], v[132:135], v[226:229], v[28:31]
	v_mfma_f32_16x16x32_bf16 v[24:27], v[140:143], v[226:229], v[24:27]
	v_mfma_f32_16x16x32_bf16 v[12:15], v[132:135], v[234:237], v[12:15]
	v_mfma_f32_16x16x32_bf16 v[8:11], v[140:143], v[234:237], v[8:11]
	s_setprio 0
	s_setprio 1
	v_mfma_f32_16x16x32_bf16 v[52:55], v[144:147], v[206:209], v[52:55]
	v_mfma_f32_16x16x32_bf16 v[48:51], v[186:189], v[206:209], v[48:51]
	v_mfma_f32_16x16x32_bf16 v[36:39], v[144:147], v[214:217], v[36:39]
	v_mfma_f32_16x16x32_bf16 v[32:35], v[186:189], v[214:217], v[32:35]
	v_mfma_f32_16x16x32_bf16 v[20:23], v[144:147], v[222:225], v[20:23]
	v_mfma_f32_16x16x32_bf16 v[16:19], v[186:189], v[222:225], v[16:19]
	v_mfma_f32_16x16x32_bf16 v[4:7], v[144:147], v[230:233], v[4:7]
	v_mfma_f32_16x16x32_bf16 v[0:3], v[186:189], v[230:233], v[0:3]
	v_mfma_f32_16x16x32_bf16 v[52:55], v[148:151], v[210:213], v[52:55]
	v_mfma_f32_16x16x32_bf16 v[48:51], v[202:205], v[210:213], v[48:51]
	v_mfma_f32_16x16x32_bf16 v[36:39], v[148:151], v[218:221], v[36:39]
	v_mfma_f32_16x16x32_bf16 v[32:35], v[202:205], v[218:221], v[32:35]
	v_mfma_f32_16x16x32_bf16 v[20:23], v[148:151], v[226:229], v[20:23]
	v_mfma_f32_16x16x32_bf16 v[16:19], v[202:205], v[226:229], v[16:19]
	v_mfma_f32_16x16x32_bf16 v[4:7], v[148:151], v[234:237], v[4:7]
	v_mfma_f32_16x16x32_bf16 v[0:3], v[202:205], v[234:237], v[0:3]
	s_setprio 0
	s_barrier
	s_add_i32 s71, s71, 2
	s_add_u32 s40, s40, 0x100
	s_addc_u32 s41, s41, 0
	s_add_u32 s31, s31, 0x100
	s_addc_u32 s35, s35, 0
	s_cmp_gt_u32 s71, 13
	s_cbranch_scc0 .LBB0_174
	.p2alignl 6, 3212836864

; #define LAS __attribute__((address_space(3)))
; __device__ __forceinline__ void na_phase(const AttnP& P, LAS unsigned char* lds, int tid, int wave, int lane, bool fast, float shift, AttStage<true>& swa_st, AttQZ& swa_qz) {
;     const int G = gridDim.x, c = blockIdx.x;
;     const int spw = (3072 + G - 1) / G;
;     const int nsteps = min(spw, max(3072 - c * spw, 0));
;     AttStage<false> rg; AttQZ qzn;
;     if (nsteps > 0) { const NaStep s0 = na_step(0, spw, c); na_load(P, s0, tid, rg); att_load_qz<false>(P, lane, s0.b * SEQ, (2 * s0.rp + (wave >> 2)) * 64 + 16 * (wave & 3), s0.h, qzn); }
; __global__ void __launch_bounds__(512, 2) fwd_kernel(Args a) {
;     ...
;         float shiftA, shiftB; bool fast;
;         { float mqa = fabsf(a.in[4][lane]), mka = fabsf(a.in[5][lane]), mqb = fabsf(a.in[7][lane]), mkb = fabsf(a.in[8][lane]), msk = fabsf(a.in[9][lane & 7]), mr = 0.f;
;           for (int i = tid; i < 8 * 465; i += 512) mr = fmaxf(mr, fabsf(a.in[6][i]));
; #pragma unroll
;           for (int o = 1; o < 64; o <<= 1) { mqa = fmaxf(mqa, __shfl_xor(mqa, o)); mka = fmaxf(mka, __shfl_xor(mka, o)); mqb = fmaxf(mqb, __shfl_xor(mqb, o)); mkb = fmaxf(mkb, __shfl_xor(mkb, o));
;               msk = fmaxf(msk, __shfl_xor(msk, o)); mr = fmaxf(mr, __shfl_xor(mr, o)); }
;           LAS float* red = (LAS float*)(lds + ATT_RPB);
;           if (lane == 0) red[wave] = mr;
;           __syncthreads();
;           mr = red[0];
; #pragma unroll
;           for (int w = 1; w < 8; ++w) mr = fmaxf(mr, red[w]);
;           __syncthreads();
;           shiftA = 1.02f * (64.f * mqa * mka * QSCALE + mr * LOG2E) + 0.5f; shiftB = 1.02f * (64.f * mqb * mkb * QSCALE) + 0.5f;
;           fast = (shiftA < 60.f) && (shiftB < 60.f) && (msk * LOG2E < 60.f); }
.LBB0_273:
.LBB0_274:
	v_mul_f32_e32 v56, 0x42800000, v56
	s_mov_b32 s0, 0x3e38aa3b
	v_mul_f32_e32 v56, v60, v56
	s_mov_b32 s1, 0x3fb8aa3b
	v_pk_mul_f32 v[56:57], v[56:57], s[0:1]
	s_mov_b32 s0, 0x3f828f5c
	v_add_f32_e32 v56, v56, v57
	v_fma_f32 v155, v56, s0, 0.5
	v_mul_f32_e32 v56, 0x42800000, v58
	v_mul_f32_e32 v56, v56, v59
	v_mul_f32_e32 v56, 0x3e38aa3b, v56
	v_fma_f32 v182, v56, s0, 0.5
	s_mov_b32 s4, 0x42700000
	v_cmp_ngt_f32_e32 vcc, s4, v155
	v_cmp_ngt_f32_e64 s[0:1], s4, v182
	v_mul_f32_e32 v56, 0x3fb8aa3b, v61
	s_or_b64 s[0:1], s[0:1], vcc
	v_cmp_ngt_f32_e32 vcc, s4, v56
	s_or_b64 s[0:1], vcc, s[0:1]
	s_add_u32 s24, s64, 0x1100000
	s_addc_u32 s25, s65, 0
	v_writelane_b32 v249, s0, 9
	s_cmp_lt_i32 s43, 2
	v_and_b32_e32 v153, 35, v190
	v_lshrrev_b32_e32 v183, 4, v191
	v_writelane_b32 v249, s1, 10
	s_cbranch_scc1 .LBB0_321
	v_lshlrev_b32_e32 v56, 4, v190
	s_movk_i32 s0, 0x70
	v_and_b32_e32 v57, 0x3f80, v56
	v_bitop3_b32 v58, v56, s0, v190 bitop3:0x48
	v_add3_u32 v164, 0, v57, v58
	v_lshrrev_b32_e32 v58, 1, v190
	v_and_b32_e32 v57, 16, v152
	v_and_b32_e32 v59, 12, v58
	s_bfe_u32 s44, s48, 0x20006
	v_or3_b32 v57, v153, v57, v59
	s_lshl_b32 s1, s44, 4
	v_and_b32_e32 v168, 15, v190
	v_and_b32_e32 v56, 0x3c00, v56
	s_add_i32 s0, 0, 0x12000
	v_lshlrev_b32_e32 v57, 4, v57
	v_or_b32_e32 v171, s1, v168
	v_add3_u32 v165, s0, v56, v57
	v_lshlrev_b32_e32 v56, 3, v190
	s_lshr_b32 s33, s48, 8
	v_sub_u32_e64 v57, v171, 8 clamp
	v_lshl_add_u32 v175, v168, 4, s0
	s_movk_i32 s0, 0x3c0
	v_and_b32_e32 v154, 56, v56
	v_lshl_or_b32 v56, s33, 6, v168
	s_cmp_eq_u32 s44, 2
	v_min_u32_e32 v172, 48, v57
	v_cmp_gt_u32_e64 s[6:7], s0, v190
	v_add_u32_e32 v57, 0x200, v190
	s_movk_i32 s0, 0x1c0
	v_add_u32_e32 v166, -16, v191
	v_mov_b32_e32 v157, 0
	v_lshrrev_b32_e32 v158, 6, v190
	v_or_b32_e32 v169, s1, v56
	v_and_b32_e32 v56, 24, v58
	s_cselect_b32 s45, 24, 32
	v_lshlrev_b32_e32 v173, 2, v183
	v_lshlrev_b32_e32 v58, 3, v183
	v_xor_b32_e32 v96, 0x80000000, v155
	v_lshrrev_b32_e32 v59, 6, v57
	v_cmp_gt_u32_e64 s[8:9], s0, v190
	s_lshl_b32 s0, s42, 1
	s_mov_b32 s39, 0
	v_cmp_gt_u32_e64 s[4:5], 31, v166
	v_lshrrev_b32_e32 v167, 3, v190
	v_mov_b32_e32 v159, v157
	v_or_b32_e32 v170, 4, v183
	v_add_u32_e32 v174, 16, v172
	v_mov_b32_e32 v97, v96
	v_mov_b32_e32 v98, v96
	v_mov_b32_e32 v99, v96
	v_or_b32_e32 v176, 1, v173
	v_or_b32_e32 v177, 2, v173
	v_or_b32_e32 v178, 3, v173
	v_mul_u32_u24_e32 v179, 31, v158
	v_add_u32_e32 v184, s10, v152
	v_mul_u32_u24_e32 v185, 31, v59
	v_lshl_add_u32 v186, v57, 2, s10
	s_lshl_b32 s12, s42, 4
	s_add_i32 s46, s43, -1
	s_add_i32 s47, s0, 2
	v_lshlrev_b32_e32 v160, 1, v56
	s_mov_b32 s49, 0xf149f2ca
	v_lshlrev_b32_e32 v162, 1, v58
	v_mov_b32_e32 v187, 0xf149f2ca
	v_mov_b32_e32 v188, 0xffff0000
	v_mov_b32_e32 v189, 0xffff
	s_mov_b32 s50, 0
	.p2alignl 6, 3212836864

; template <bool SWA, bool FAST>
; __device__ __forceinline__ void att_tile(const AttnP& P, LAS unsigned char* lds, int lane, int tb, int qpos0, int hq, int kloc0, int r, int ct, int kr0, int kc0, const AttQZ& qz, float shift) {
;     ...
;         const int qp = qpos0 + li;
; #pragma unroll
;         for (int s = 0; s < NSEG; ++s) {
;             const int kb0 = qpos0 - 128 + 32 * s;
;             if (s >= 1 && s <= 7 && kb0 >= 0 && kb0 + 31 < SEQ) {
; #pragma unroll
;                 for (int kt = 0; kt < 2; ++kt)
; #pragma unroll
;                     for (int j = 0; j < 4; ++j) { if (!FAST) mx = fmaxf(mx, sc[s][kt][j]); }
;             } else {
;                 asm volatile("");
; #pragma unroll
;                 for (int kt = 0; kt < 2; ++kt)
; #pragma unroll
;                     for (int j = 0; j < 4; ++j) { const int kp = kb0 + 16 * kt + 4 * fq + j; const int d = kp - qp;
;                         const bool ok = (kp >= 0) && (kp < SEQ) && (d <= 128) && (d >= -128);
;                         const float v = ok ? sc[s][kt][j] : -1e30f; sc[s][kt][j] = v; if (!FAST) mx = fmaxf(mx, v); }
;             }
.LBB0_371:
	s_and_b32 s2, s5, 0xfffff000
	s_and_b32 s3, s8, 0xf80
	s_or_b32 s2, s3, s2
	v_add_u32_e32 v60, s2, v197
	s_lshl_b32 s2, s0, 4
	v_writelane_b32 v249, s5, 46
	s_and_b32 s11, s2, 0x200
	v_writelane_b32 v249, s8, 47
	v_ashrrev_i32_e32 v61, 31, v60
	s_add_u32 s2, s64, s11
	v_lshlrev_b64 v[72:73], 10, v[60:61]
	s_addc_u32 s3, s65, 0
	v_readlane_b32 s12, v249, 0
	v_lshl_add_u64 v[172:173], s[2:3], 0, v[72:73]
	s_lshr_b32 s2, s0, 1
	v_readlane_b32 s14, v249, 2
	v_readlane_b32 s15, v249, 3
	s_and_b32 s2, s2, 16
	s_mov_b64 s[6:7], s[14:15]
	s_add_u32 s2, s6, s2
	v_readlane_b32 s13, v249, 1
	s_addc_u32 s3, s7, 0
	s_lshl_b32 s0, s0, 7
	s_and_b32 s13, s0, 0xf80
	v_readlane_b32 s0, v249, 39
	s_add_i32 s13, s13, s0
	s_add_i32 s0, s13, 0xffffff80
	v_or_b32_e32 v63, s13, v196
	v_or_b32_e32 v72, s0, v199
	s_add_i32 s12, s1, s4
	v_sub_u32_e32 v73, v72, v63
	s_cmpk_lt_u32 s0, 0x1000
	v_add_u32_e32 v74, 0x80, v73
	v_readlane_b32 s16, v249, 4
	v_readlane_b32 s17, v249, 5
	s_cselect_b64 s[0:1], -1, 0
	v_cmp_gt_u32_e32 vcc, s33, v74
	v_add_u32_e32 v74, 0x81, v73
	v_readlane_b32 s18, v249, 6
	v_readlane_b32 s19, v249, 7
	s_and_b64 s[16:17], s[0:1], vcc
	v_cmp_gt_u32_e32 vcc, s33, v74
	v_add_u32_e32 v74, 0x82, v73
	s_and_b64 s[18:19], s[0:1], vcc
	v_cmp_gt_u32_e32 vcc, s33, v74
	v_add_u32_e32 v74, 0x83, v73
	s_and_b64 s[20:21], s[0:1], vcc
	v_cmp_gt_u32_e32 vcc, s33, v74
	s_and_b64 s[22:23], s[0:1], vcc
	s_add_i32 s0, s13, 0xffffff90
	s_cmpk_lt_u32 s0, 0x1000
	v_add_u32_e32 v74, 0x90, v73
	s_cselect_b64 s[0:1], -1, 0
	v_cmp_gt_u32_e32 vcc, s33, v74
	v_add_u32_e32 v74, 17, v72
	s_movk_i32 s4, 0x1000
	s_and_b64 s[24:25], s[0:1], vcc
	v_cmp_gt_u32_e32 vcc, s4, v74
	v_add_u32_e32 v74, 0x91, v73
	v_cmp_gt_u32_e64 s[0:1], s33, v74
	v_add_u32_e32 v74, 18, v72
	s_and_b64 s[26:27], vcc, s[0:1]
	v_cmp_gt_u32_e32 vcc, s4, v74
	v_add_u32_e32 v74, 0x92, v73
	v_cmp_gt_u32_e64 s[0:1], s33, v74
	v_add_u32_e32 v72, 19, v72
	s_and_b64 s[28:29], vcc, s[0:1]
	v_cmp_gt_u32_e32 vcc, s4, v72
	v_add_u32_e32 v72, 0x93, v73
	v_cmp_gt_u32_e64 s[0:1], s33, v72
	s_and_b64 s[30:31], vcc, s[0:1]
	s_add_i32 s0, s13, 0xffffffa0
	v_or_b32_e32 v72, s0, v199
	s_cmpk_gt_u32 s0, 0xfe0
	v_sub_u32_e32 v73, v72, v63
	s_cselect_b64 s[68:69], -1, 0
	s_cmpk_lt_u32 s0, 0x1000
	v_add_u32_e32 v74, 0x80, v73
	s_cselect_b64 s[0:1], -1, 0
	v_cmp_gt_u32_e32 vcc, s33, v74
	s_and_b64 s[6:7], s[0:1], vcc
	v_add_u32_e32 v74, 0x81, v73
	v_writelane_b32 v249, s6, 48
	v_cmp_gt_u32_e32 vcc, s33, v74
	v_add_u32_e32 v74, 0x82, v73
	v_writelane_b32 v249, s7, 49
	s_and_b64 s[6:7], s[0:1], vcc
	v_writelane_b32 v249, s6, 50
	v_cmp_gt_u32_e32 vcc, s33, v74
	v_add_u32_e32 v74, 0x83, v73
	v_writelane_b32 v249, s7, 51
	s_and_b64 s[6:7], s[0:1], vcc
	v_writelane_b32 v249, s6, 52
	v_cmp_gt_u32_e32 vcc, s33, v74
	s_and_b64 s[0:1], s[0:1], vcc
	v_writelane_b32 v249, s7, 53
	v_writelane_b32 v249, s0, 54
	v_add_u32_e32 v74, 0x90, v73
	v_cmp_gt_u32_e32 vcc, s33, v74
	v_writelane_b32 v249, s1, 55
	s_add_i32 s0, s13, 0xffffffb0
	s_cmpk_lt_u32 s0, 0x1000
	s_cselect_b64 s[0:1], -1, 0
	s_and_b64 s[0:1], s[0:1], vcc
	v_add_u32_e32 v74, 17, v72
	v_writelane_b32 v249, s0, 56
	v_cmp_gt_u32_e32 vcc, s4, v74
	v_add_u32_e32 v74, 0x91, v73
	v_writelane_b32 v249, s1, 57
	v_cmp_gt_u32_e64 s[0:1], s33, v74
	s_and_b64 s[0:1], vcc, s[0:1]
	v_add_u32_e32 v74, 18, v72
	v_writelane_b32 v249, s0, 58
	v_cmp_gt_u32_e32 vcc, s4, v74
	v_add_u32_e32 v74, 0x92, v73
	v_writelane_b32 v249, s1, 59
	v_cmp_gt_u32_e64 s[0:1], s33, v74
	s_and_b64 s[0:1], vcc, s[0:1]
	v_add_u32_e32 v72, 19, v72
	v_writelane_b32 v249, s0, 60
	v_cmp_gt_u32_e32 vcc, s4, v72
	v_add_u32_e32 v72, 0x93, v73
	v_writelane_b32 v249, s1, 61
	v_cmp_gt_u32_e64 s[0:1], s33, v72
	s_and_b64 s[0:1], vcc, s[0:1]
	s_movk_i32 s50, 0xfee
	v_writelane_b32 v249, s0, 62
	s_movk_i32 s52, 0xfed
	v_lshlrev_b64 v[60:61], 11, v[60:61]
	v_writelane_b32 v249, s1, 63
	s_sub_i32 s0, s13, 64
	v_or_b32_e32 v72, s0, v199
	s_cmpk_gt_u32 s0, 0xfe0
	v_sub_u32_e32 v73, v72, v63
	s_cselect_b64 s[70:71], -1, 0
	s_cmpk_lt_u32 s0, 0x1000
	v_add_u32_e32 v74, 0x80, v73
	s_cselect_b64 s[0:1], -1, 0
	v_cmp_gt_u32_e32 vcc, s33, v74
	s_and_b64 s[6:7], s[0:1], vcc
	v_add_u32_e32 v74, 0x81, v73
	v_writelane_b32 v248, s6, 0
	v_cmp_gt_u32_e32 vcc, s33, v74
	v_add_u32_e32 v74, 0x82, v73
	v_writelane_b32 v248, s7, 1
	s_and_b64 s[6:7], s[0:1], vcc
	v_writelane_b32 v248, s6, 2
	v_cmp_gt_u32_e32 vcc, s33, v74
	v_add_u32_e32 v74, 0x83, v73
	v_writelane_b32 v248, s7, 3
	s_and_b64 s[6:7], s[0:1], vcc
	v_writelane_b32 v248, s6, 4
	v_cmp_gt_u32_e32 vcc, s33, v74
	s_and_b64 s[0:1], s[0:1], vcc
	v_writelane_b32 v248, s7, 5
	v_writelane_b32 v248, s0, 6
	v_add_u32_e32 v74, 0x90, v73
	v_cmp_gt_u32_e32 vcc, s33, v74
	v_writelane_b32 v248, s1, 7
	s_sub_i32 s0, s13, 48
	s_cmpk_lt_u32 s0, 0x1000
	s_cselect_b64 s[0:1], -1, 0
	s_and_b64 s[0:1], s[0:1], vcc
	v_writelane_b32 v248, s0, 8
	v_add_u32_e32 v74, 17, v72
	v_add_u32_e32 v75, 0x91, v73
	v_writelane_b32 v248, s1, 9
	v_cmp_gt_u32_e32 vcc, s4, v74
	v_cmp_gt_u32_e64 s[0:1], s33, v75
	s_and_b64 s[0:1], vcc, s[0:1]
	v_add_u32_e32 v74, 18, v72
; template <bool SWA, bool FAST>
; __device__ __forceinline__ void att_tile(const AttnP& P, LAS unsigned char* lds, int lane, int tb, int qpos0, int hq, int kloc0, int r, int ct, int kr0, int kc0, const AttQZ& qz, float shift) {
;     ...
;         const int qp = qpos0 + li;
; #pragma unroll
;         for (int s = 0; s < NSEG; ++s) {
;             const int kb0 = qpos0 - 128 + 32 * s;
;             if (s >= 1 && s <= 7 && kb0 >= 0 && kb0 + 31 < SEQ) {
; #pragma unroll
;                 for (int kt = 0; kt < 2; ++kt)
; #pragma unroll
;                     for (int j = 0; j < 4; ++j) { if (!FAST) mx = fmaxf(mx, sc[s][kt][j]); }
;             } else {
;                 asm volatile("");
; #pragma unroll
;                 for (int kt = 0; kt < 2; ++kt)
; #pragma unroll
;                     for (int j = 0; j < 4; ++j) { const int kp = kb0 + 16 * kt + 4 * fq + j; const int d = kp - qp;
;                         const bool ok = (kp >= 0) && (kp < SEQ) && (d <= 128) && (d >= -128);
;                         const float v = ok ? sc[s][kt][j] : -1e30f; sc[s][kt][j] = v; if (!FAST) mx = fmaxf(mx, v); }
;             }
; template <bool SWA>
; __device__ __forceinline__ void att_phase(const AttnP& P, LAS unsigned char* lds, int tid, int wave, int lane, bool fast, float shift, AttStage<SWA>& st, AttQZ& qzn, bool pre) {
;     ...
;         const int tb = b * SEQ;
;         if (SWA) {
; #pragma unroll 1
;             for (int j = 0; j < 4; ++j) { int kl = 16 * wave; asm volatile("" : "+v"(kl));
;                 const AttQZ qz = qzn;
;                 if (j < 3) att_load_qz<true>(P, lane, tb, ATT_QPOS(x), 4 * h + j + 1, qzn);
;                 else if (has_next) att_load_qz<true>(P, lane, nb * SEQ, ATT_QPOS(nx), 4 * nh, qzn);
;                 if (fast) att_tile<true, true>(P, lds, lane, tb, 128 * x + 16 * wave, 4 * h + j, kl, 0, 0, 0, 0, qz, shift);
	v_writelane_b32 v248, s0, 10
	v_add_u32_e32 v75, 0x92, v73
	v_cmp_gt_u32_e32 vcc, s4, v74
	v_writelane_b32 v248, s1, 11
	v_cmp_gt_u32_e64 s[0:1], s33, v75
	s_and_b64 s[0:1], vcc, s[0:1]
	v_add_u32_e32 v72, 19, v72
	v_writelane_b32 v248, s0, 12
	v_add_u32_e32 v73, 0x93, v73
	v_cmp_gt_u32_e32 vcc, s4, v72
	v_writelane_b32 v248, s1, 13
	v_cmp_gt_u32_e64 s[0:1], s33, v73
	s_and_b64 s[0:1], vcc, s[0:1]
	v_readlane_b32 s8, v249, 27
	v_writelane_b32 v248, s0, 14
	v_readlane_b32 s9, v249, 28
	v_or_b32_e32 v60, s11, v60
	v_writelane_b32 v248, s1, 15
	s_sub_i32 s0, s13, 32
	v_or_b32_e32 v72, s0, v199
	s_cmpk_gt_u32 s0, 0xfe0
	v_sub_u32_e32 v73, v72, v63
	s_cselect_b64 s[72:73], -1, 0
	s_cmpk_lt_u32 s0, 0x1000
	v_add_u32_e32 v74, 0x80, v73
	s_cselect_b64 s[0:1], -1, 0
	v_cmp_gt_u32_e32 vcc, s33, v74
	s_and_b64 s[6:7], s[0:1], vcc
	v_add_u32_e32 v74, 0x81, v73
	v_writelane_b32 v248, s6, 16
	v_cmp_gt_u32_e32 vcc, s33, v74
	v_add_u32_e32 v74, 0x82, v73
	v_writelane_b32 v248, s7, 17
	s_and_b64 s[6:7], s[0:1], vcc
	v_writelane_b32 v248, s6, 18
	v_cmp_gt_u32_e32 vcc, s33, v74
	v_add_u32_e32 v74, 0x83, v73
	v_writelane_b32 v248, s7, 19
	s_and_b64 s[6:7], s[0:1], vcc
	v_writelane_b32 v248, s6, 20
	v_cmp_gt_u32_e32 vcc, s33, v74
	s_and_b64 s[0:1], s[0:1], vcc
	v_writelane_b32 v248, s7, 21
	v_writelane_b32 v248, s0, 22
	v_add_u32_e32 v74, 0x90, v73
	v_cmp_gt_u32_e32 vcc, s33, v74
	v_writelane_b32 v248, s1, 23
	s_add_i32 s0, s13, -16
	s_cmpk_lt_u32 s0, 0x1000
	s_cselect_b64 s[0:1], -1, 0
	s_and_b64 s[0:1], s[0:1], vcc
	v_writelane_b32 v248, s0, 24
	v_add_u32_e32 v74, 17, v72
	v_add_u32_e32 v75, 0x91, v73
	v_writelane_b32 v248, s1, 25
	v_cmp_gt_u32_e32 vcc, s4, v74
	v_cmp_gt_u32_e64 s[0:1], s33, v75
	s_and_b64 s[0:1], vcc, s[0:1]
	v_add_u32_e32 v74, 18, v72
	v_writelane_b32 v248, s0, 26
	v_add_u32_e32 v75, 0x92, v73
	v_cmp_gt_u32_e32 vcc, s4, v74
	v_writelane_b32 v248, s1, 27
	v_cmp_gt_u32_e64 s[0:1], s33, v75
	s_and_b64 s[0:1], vcc, s[0:1]
	v_add_u32_e32 v72, 19, v72
	v_writelane_b32 v248, s0, 28
	v_add_u32_e32 v73, 0x93, v73
	v_cmp_gt_u32_e32 vcc, s4, v72
	v_writelane_b32 v248, s1, 29
	v_cmp_gt_u32_e64 s[0:1], s33, v73
	s_and_b64 s[0:1], vcc, s[0:1]
	v_or_b32_e32 v74, s13, v199
	s_cmpk_gt_u32 s13, 0xfe0
	v_sub_u32_e32 v63, v74, v63
	s_cselect_b64 s[74:75], -1, 0
	s_cmpk_lt_u32 s13, 0x1000
	v_add_u32_e32 v72, 0x81, v63
	v_writelane_b32 v248, s0, 30
	s_cselect_b64 s[82:83], -1, 0
	v_cmp_gt_u32_e32 vcc, s33, v72
	v_writelane_b32 v248, s1, 31
	s_and_b64 s[0:1], s[82:83], vcc
	v_add_u32_e32 v72, 0x82, v63
	v_writelane_b32 v248, s0, 32
	v_cmp_gt_u32_e32 vcc, s33, v72
	v_add_u32_e32 v63, 0x83, v63
	v_writelane_b32 v248, s1, 33
	s_and_b64 s[0:1], s[82:83], vcc
	v_cmp_gt_u32_e32 vcc, s33, v63
	s_and_b64 s[88:89], s[82:83], vcc
	s_cmpk_lt_u32 s13, 0xff0
	s_cselect_b64 s[90:91], -1, 0
	s_cmpk_gt_u32 s13, 0xfc0
	s_cselect_b64 s[76:77], -1, 0
	s_cmpk_lt_u32 s13, 0xfe0
	s_cselect_b64 s[92:93], -1, 0
	s_cmpk_lt_u32 s13, 0xfd0
	s_cselect_b64 s[94:95], -1, 0
	s_cmpk_gt_u32 s13, 0xfa0
	s_cselect_b64 s[78:79], -1, 0
	s_cmpk_lt_u32 s13, 0xfc0
	s_cselect_b64 s[96:97], -1, 0
	s_cmpk_lt_u32 s13, 0xfb0
	s_cselect_b64 s[58:59], -1, 0
	s_cmpk_gt_u32 s13, 0xf80
	v_add_u32_e32 v63, s13, v203
	s_cselect_b64 s[80:81], -1, 0
	s_cmpk_lt_u32 s13, 0xfa0
	v_readlane_b32 s6, v249, 25
	v_writelane_b32 v248, s0, 34
	s_cselect_b64 s[4:5], -1, 0
	s_cmpk_lt_u32 s13, 0xf90
	v_cmp_gt_u32_e32 vcc, s50, v63
	v_readlane_b32 s7, v249, 26
	v_writelane_b32 v248, s1, 35
	s_cselect_b64 s[0:1], -1, 0
	s_and_b64 s[6:7], vcc, s[6:7]
	v_cmp_gt_u32_e32 vcc, s52, v63
	s_and_b64 s[8:9], vcc, s[8:9]
	s_cmpk_lt_u32 s13, 0xf80
	s_cselect_b64 s[34:35], -1, 0
	s_lshl_b32 s38, s10, 1
	v_add_u32_e32 v72, s12, v197
	v_add_u32_e32 v75, s13, v201
	v_add_u32_e32 v76, s13, v202
	v_readlane_b32 s10, v249, 29
	v_readlane_b32 s12, v249, 31
	v_readlane_b32 s14, v249, 33
	v_readlane_b32 s36, v249, 35
	v_readlane_b32 s11, v249, 30
	v_readlane_b32 s13, v249, 32
	v_readlane_b32 s15, v249, 34
	v_readlane_b32 s37, v249, 36
	v_ashrrev_i32_e32 v73, 31, v72
	s_and_b64 s[10:11], s[34:35], s[10:11]
	s_and_b64 s[12:13], s[34:35], s[12:13]
	s_and_b64 s[14:15], s[34:35], s[14:15]
	s_and_b64 s[34:35], s[34:35], s[36:37]
	v_readlane_b32 s36, v249, 13
	v_lshl_add_u64 v[174:175], v[170:171], 0, v[60:61]
	v_lshlrev_b64 v[60:61], 10, v[72:73]
	v_readlane_b32 s37, v249, 14
	s_movk_i32 s54, 0xfef
	v_cmp_gt_u32_e64 s[40:41], s52, v74
	v_lshl_add_u64 v[72:73], s[36:37], 0, v[60:61]
	v_readlane_b32 s36, v249, 15
	v_readlane_b32 s37, v249, 16
	v_lshl_add_u64 v[176:177], v[72:73], 0, s[38:39]
	v_cmp_gt_u32_e64 s[42:43], s54, v75
	v_lshl_add_u64 v[60:61], s[36:37], 0, v[60:61]
	s_mov_b32 s37, s39
	v_writelane_b32 v248, s36, 36
	v_lshl_add_u64 v[178:179], v[60:61], 0, s[38:39]
	v_cmp_gt_u32_e64 s[38:39], s50, v74
	v_writelane_b32 v248, s37, 37
	v_cmp_gt_u32_e64 s[36:37], s54, v74
	v_cmp_gt_u32_e64 s[44:45], s50, v75
	v_cmp_gt_u32_e64 s[46:47], s52, v75
	v_cmp_gt_u32_e64 s[48:49], s54, v76
	v_cmp_gt_u32_e64 s[50:51], s50, v76
	v_cmp_gt_u32_e64 s[52:53], s52, v76
	v_cmp_gt_u32_e64 s[54:55], s54, v63
	.p2alignl 6, 3212836864

; template <class Epi, class Sched>
; __device__ __forceinline__ void gemm_phase(LAS unsigned char* lds, const Sched& S, const Epi& E, bool natural = false) {
;     ...
;         const bool has_next = S.next(ui + 1, nxt);
;         const char* nA = cA; const char* nB = cB; if (has_next) S.ptrs(nxt, nA, nB);
;     ...
; #pragma unroll
;         for (int a = 0; a < 2; ++a)
; #pragma unroll
;             for (int b = 0; b < 2; ++b)
; #pragma unroll
;                 for (int m = 0; m < 4; ++m)
; #pragma unroll
;                     for (int n = 0; n < 2; ++n) acc[a][b][m][n] = (f32x4){0.f, 0.f, 0.f, 0.f};
;         cur = nxt; cA = nA; cB = nB; ++ui;
.LBB0_490:
	s_ashr_i32 s19, s18, 31
	s_ashr_i32 s17, s16, 31
	s_lshl_b64 s[20:21], s[18:19], 19
	s_lshl_b64 s[22:23], s[16:17], 19
	s_add_u32 s20, s3, s20
	s_addc_u32 s21, s33, s21
	s_add_u32 s22, s34, s22
	s_addc_u32 s23, s35, s23
	s_and_b64 s[30:31], s[0:1], exec
	s_cselect_b32 s17, s21, s25
	s_cselect_b32 s19, s20, s24
	s_cselect_b32 s55, s23, s29
	s_cselect_b32 s56, s22, s28
	s_lshl_b32 s27, s27, 9
	s_lshl_b32 s26, s26, 19
	s_add_i32 s26, s26, s27
	v_mov_b32_e32 v2, v177
	v_mov_b32_e32 v3, v177
	s_add_u32 s57, s28, 0x100
	v_mov_b32_e32 v0, v177
	v_mov_b32_e32 v1, v177
	v_mov_b64_e32 v[6:7], v[2:3]
	v_mov_b64_e32 v[18:19], v[2:3]
	v_mov_b64_e32 v[22:23], v[2:3]
	v_mov_b64_e32 v[34:35], v[2:3]
	v_mov_b64_e32 v[38:39], v[2:3]
	v_mov_b64_e32 v[50:51], v[2:3]
	v_mov_b64_e32 v[54:55], v[2:3]
	v_mov_b64_e32 v[10:11], v[2:3]
	v_mov_b64_e32 v[14:15], v[2:3]
	v_mov_b64_e32 v[26:27], v[2:3]
	v_mov_b64_e32 v[30:31], v[2:3]
	v_mov_b64_e32 v[42:43], v[2:3]
	v_mov_b64_e32 v[46:47], v[2:3]
	v_mov_b64_e32 v[58:59], v[2:3]
	v_mov_b64_e32 v[62:63], v[2:3]
	v_mov_b64_e32 v[66:67], v[2:3]
	v_mov_b64_e32 v[70:71], v[2:3]
	v_mov_b64_e32 v[82:83], v[2:3]
	v_mov_b64_e32 v[86:87], v[2:3]
	v_mov_b64_e32 v[98:99], v[2:3]
	v_mov_b64_e32 v[102:103], v[2:3]
	v_mov_b64_e32 v[114:115], v[2:3]
	v_mov_b64_e32 v[118:119], v[2:3]
	v_mov_b64_e32 v[74:75], v[2:3]
	v_mov_b64_e32 v[78:79], v[2:3]
	v_mov_b64_e32 v[90:91], v[2:3]
	v_mov_b64_e32 v[94:95], v[2:3]
	v_mov_b64_e32 v[106:107], v[2:3]
	v_mov_b64_e32 v[110:111], v[2:3]
	v_mov_b64_e32 v[122:123], v[2:3]
	v_mov_b64_e32 v[126:127], v[2:3]
	v_add_u32_e32 v176, s26, v187
	v_lshl_add_u64 v[160:161], s[24:25], 0, v[178:179]
	v_lshl_add_u64 v[162:163], s[24:25], 0, v[180:181]
	s_addc_u32 s58, s29, 0
	s_mov_b32 s59, -2
	s_mov_b64 s[26:27], 0
	v_mov_b64_e32 v[4:5], v[0:1]
	v_mov_b64_e32 v[16:17], v[0:1]
	v_mov_b64_e32 v[20:21], v[0:1]
	v_mov_b64_e32 v[32:33], v[0:1]
	v_mov_b64_e32 v[36:37], v[0:1]
	v_mov_b64_e32 v[48:49], v[0:1]
	v_mov_b64_e32 v[52:53], v[0:1]
	v_mov_b64_e32 v[8:9], v[0:1]
	v_mov_b64_e32 v[12:13], v[0:1]
	v_mov_b64_e32 v[24:25], v[0:1]
	v_mov_b64_e32 v[28:29], v[0:1]
	v_mov_b64_e32 v[40:41], v[0:1]
	v_mov_b64_e32 v[44:45], v[0:1]
	v_mov_b64_e32 v[56:57], v[0:1]
	v_mov_b64_e32 v[60:61], v[0:1]
	v_mov_b64_e32 v[64:65], v[0:1]
	v_mov_b64_e32 v[68:69], v[0:1]
	v_mov_b64_e32 v[80:81], v[0:1]
	v_mov_b64_e32 v[84:85], v[0:1]
	v_mov_b64_e32 v[96:97], v[0:1]
	v_mov_b64_e32 v[100:101], v[0:1]
	v_mov_b64_e32 v[112:113], v[0:1]
	v_mov_b64_e32 v[116:117], v[0:1]
	v_mov_b64_e32 v[72:73], v[0:1]
	v_mov_b64_e32 v[76:77], v[0:1]
	v_mov_b64_e32 v[88:89], v[0:1]
	v_mov_b64_e32 v[92:93], v[0:1]
	v_mov_b64_e32 v[104:105], v[0:1]
	v_mov_b64_e32 v[108:109], v[0:1]
	v_mov_b64_e32 v[120:121], v[0:1]
	v_mov_b64_e32 v[124:125], v[0:1]
	s_branch .LBB0_492
	.p2alignl 6, 3212836864

; #define PG8_STAGE(bufoff, gbase, voff) do { _Pragma("unroll") for (int _i = 0; _i < 2; ++_i) \
;         __builtin_amdgcn_global_load_lds((const unsigned*)((const char*)(gbase) + (voff)[_i]), (LAS unsigned*)(lds + (bufoff) + ldsw + _i * 8192), 16, 0, 0); } while (0)
; #define PG8_LDA(dst, b, h) do { _Pragma("unroll") for (int m = 0; m < 4; ++m) _Pragma("unroll") for (int k = 0; k < 2; ++k) dst[m][k] = *(const LAS bf16x8*)(lds + PG8_SA(b, h) + aoff + m * 2048 + k * 1024); } while (0)
; #define PG8_LDB(dst, b, h) do { _Pragma("unroll") for (int n = 0; n < 2; ++n) _Pragma("unroll") for (int k = 0; k < 2; ++k) dst[n][k] = *(const LAS bf16x8*)(lds + PG8_SB(b, h) + boff + n * 2048 + k * 1024); } while (0)
; #define PG8_MMA(ai, bj, At, Bt) do { __builtin_amdgcn_s_setprio(1); _Pragma("unroll") for (int m = 0; m < 4; ++m) _Pragma("unroll") for (int n = 0; n < 2; ++n) _Pragma("unroll") for (int k = 0; k < 2; ++k) \
;         acc[ai][bj][m][n] = __builtin_amdgcn_mfma_f32_16x16x32_bf16(Bt[n][k], At[m][k], acc[ai][bj][m][n], 0, 0, 0); __builtin_amdgcn_s_setprio(0); } while (0)
; #define PG8_WAIT_V(n) asm volatile("s_waitcnt vmcnt(" #n ")" ::: "memory")
; #define PG8_WAIT_L(n) asm volatile("s_waitcnt lgkmcnt(" #n ")" ::: "memory")
; #define PG8_BAR __builtin_amdgcn_s_barrier()
; template <class Epi, class Sched>
; __device__ __forceinline__ void gemm_phase(LAS unsigned char* lds, const Sched& S, const Epi& E, bool natural = false) {
;     ...
;         const char* nA = cA; const char* nB = cB; if (has_next) S.ptrs(nxt, nA, nB);
;         for (int t = 0; t < nt; t += 2) {
;             const bool last = (t == nt - 2);
;             const char* a1 = cA + (size_t)(t + 1) * kstep;
;             const char* a2 = last ? nA : cA + (size_t)(t + 2) * kstep; const char* b2 = last ? nB : cB + (size_t)(t + 2) * kstep;
;             const char* a3 = a2 + kstep; const char* b3 = b2 + kstep;
;             if constexpr (Epi::MIDHOOK) { if (t == nt / 2) E.mid(acc, cur, wr, wc, fr, fq); }
;             PG8_LDB(B0, 0, 0); PG8_LDB(B1, 0, 1); PG8_SCHED; PG8_LDA(At, 0, 0); PG8_STAGE(PG8_SA(1, 1), a1 + hstep, voffA);
;             PG8_WAIT_V(8); PG8_WAIT_L(0); PG8_BAR; PG8_MMA(0, 0, At, B0); PG8_MMA(0, 1, At, B1); PG8_BAR; PG8_SCHED;
;             PG8_LDA(At, 0, 1); PG8_STAGE(PG8_SB(0, 0), b2, voffB0); PG8_STAGE(PG8_SB(0, 1), b2, voffB1); PG8_STAGE(PG8_SA(0, 0), a2, voffA);
.LBB0_563:
	s_ashr_i32 s15, s14, 31
	s_ashr_i32 s13, s12, 31
	s_lshl_b64 s[16:17], s[14:15], 19
	s_lshl_b64 s[18:19], s[12:13], 19
	s_add_u32 s16, s3, s16
	s_addc_u32 s17, s28, s17
	s_add_u32 s18, s29, s18
	s_addc_u32 s19, s30, s19
	s_and_b64 s[24:25], s[0:1], exec
	s_cselect_b32 s13, s17, s21
	s_cselect_b32 s15, s16, s20
	s_cselect_b32 s26, s19, s23
	s_cselect_b32 s27, s18, s22
	s_add_u32 s20, s20, 0x40080
	s_addc_u32 s21, s21, 0
	s_add_u32 s54, s22, 0x100
	s_addc_u32 s55, s23, 0
	s_mov_b32 s56, -2
	ds_read_b128 v[150:153], v156
	ds_read_b128 v[160:163], v156 offset:1024
	ds_read_b128 v[164:167], v156 offset:2048
	ds_read_b128 v[168:171], v156 offset:3072
	ds_read_b128 v[172:175], v157
	ds_read_b128 v[176:179], v157 offset:1024
	ds_read_b128 v[180:183], v157 offset:2048
	ds_read_b128 v[184:187], v157 offset:3072
	s_add_u32 s22, s20, 0xfffc0080
	s_addc_u32 s23, s21, -1
	s_cmp_eq_u32 s56, 12
	s_cselect_b32 s25, s13, s23
	s_cselect_b32 s24, s15, s22
	s_cselect_b32 s23, s26, s55
	s_cselect_b32 s22, s27, s54
	v_lshl_add_u64 v[220:221], s[20:21], 0, v[142:143]
	s_add_i32 m0, s35, 0xc000
	ds_read_b128 v[188:191], v158
	ds_read_b128 v[192:195], v158 offset:1024
	ds_read_b128 v[196:199], v158 offset:2048
	ds_read_b128 v[200:203], v158 offset:3072
	ds_read_b128 v[204:207], v158 offset:4096
	ds_read_b128 v[208:211], v158 offset:5120
	ds_read_b128 v[212:215], v158 offset:6144
	ds_read_b128 v[216:219], v158 offset:7168
	global_load_lds_dwordx4 v[220:221], off
	v_lshl_add_u64 v[220:221], s[20:21], 0, v[144:145]
	s_add_i32 m0, s35, 0xe000
	s_nop 0
	global_load_lds_dwordx4 v[220:221], off
	s_waitcnt vmcnt(8)
	s_waitcnt lgkmcnt(0)
	s_barrier
	s_setprio 1
	s_waitcnt lgkmcnt(0)
	v_mfma_f32_16x16x32_bf16 v[124:127], v[150:153], v[188:191], 0
	v_mfma_f32_16x16x32_bf16 v[120:123], v[164:167], v[188:191], 0
	v_mfma_f32_16x16x32_bf16 v[116:119], v[150:153], v[196:199], 0
	v_mfma_f32_16x16x32_bf16 v[112:115], v[164:167], v[196:199], 0
	v_mfma_f32_16x16x32_bf16 v[104:107], v[150:153], v[204:207], 0
	v_mfma_f32_16x16x32_bf16 v[96:99], v[164:167], v[204:207], 0
	v_mfma_f32_16x16x32_bf16 v[88:91], v[150:153], v[212:215], 0
	v_mfma_f32_16x16x32_bf16 v[80:83], v[164:167], v[212:215], 0
	v_mfma_f32_16x16x32_bf16 v[124:127], v[160:163], v[192:195], v[124:127]
	v_mfma_f32_16x16x32_bf16 v[120:123], v[168:171], v[192:195], v[120:123]
	v_mfma_f32_16x16x32_bf16 v[116:119], v[160:163], v[200:203], v[116:119]
	v_mfma_f32_16x16x32_bf16 v[112:115], v[168:171], v[200:203], v[112:115]
	v_mfma_f32_16x16x32_bf16 v[104:107], v[160:163], v[208:211], v[104:107]
	v_mfma_f32_16x16x32_bf16 v[96:99], v[168:171], v[208:211], v[96:99]
	v_mfma_f32_16x16x32_bf16 v[88:91], v[160:163], v[216:219], v[88:91]
	v_mfma_f32_16x16x32_bf16 v[80:83], v[168:171], v[216:219], v[80:83]
	s_setprio 0
	s_setprio 1
	v_mfma_f32_16x16x32_bf16 v[108:111], v[172:175], v[188:191], 0
	v_mfma_f32_16x16x32_bf16 v[100:103], v[180:183], v[188:191], 0
	v_mfma_f32_16x16x32_bf16 v[92:95], v[172:175], v[196:199], 0
	v_mfma_f32_16x16x32_bf16 v[84:87], v[180:183], v[196:199], 0
	v_mfma_f32_16x16x32_bf16 v[76:79], v[172:175], v[204:207], 0
	v_mfma_f32_16x16x32_bf16 v[72:75], v[180:183], v[204:207], 0
	v_mfma_f32_16x16x32_bf16 v[68:71], v[172:175], v[212:215], 0
	v_mfma_f32_16x16x32_bf16 v[64:67], v[180:183], v[212:215], 0
	v_mfma_f32_16x16x32_bf16 v[108:111], v[176:179], v[192:195], v[108:111]
	v_mfma_f32_16x16x32_bf16 v[100:103], v[184:187], v[192:195], v[100:103]
	v_mfma_f32_16x16x32_bf16 v[92:95], v[176:179], v[200:203], v[92:95]
	v_mfma_f32_16x16x32_bf16 v[84:87], v[184:187], v[200:203], v[84:87]
	v_mfma_f32_16x16x32_bf16 v[76:79], v[176:179], v[208:211], v[76:79]
	v_mfma_f32_16x16x32_bf16 v[72:75], v[184:187], v[208:211], v[72:75]
	v_mfma_f32_16x16x32_bf16 v[68:71], v[176:179], v[216:219], v[68:71]
	v_mfma_f32_16x16x32_bf16 v[64:67], v[184:187], v[216:219], v[64:67]
	s_setprio 0
	s_barrier
	s_add_i32 s57, s44, s31
	v_lshl_add_u64 v[220:221], s[22:23], 0, v[136:137]
	s_mov_b32 m0, s57
	ds_read_b128 v[188:191], v158 offset:16384
	ds_read_b128 v[192:195], v158 offset:17408
	ds_read_b128 v[196:199], v158 offset:18432
	ds_read_b128 v[200:203], v158 offset:19456
	ds_read_b128 v[204:207], v158 offset:20480
	ds_read_b128 v[208:211], v158 offset:21504
	ds_read_b128 v[212:215], v158 offset:22528
	ds_read_b128 v[216:219], v158 offset:23552
	global_load_lds_dwordx4 v[220:221], off
	v_lshl_add_u64 v[222:223], s[22:23], 0, v[130:131]
	s_add_i32 m0, s57, 0x2000
	s_add_i32 s57, s45, s31
	global_load_lds_dwordx4 v[222:223], off
	v_lshl_add_u64 v[224:225], s[22:23], 0, v[134:135]
	s_mov_b32 m0, s57
	v_lshl_add_u64 v[226:227], s[24:25], 0, v[132:133]
	global_load_lds_dwordx4 v[224:225], off
	v_lshl_add_u64 v[224:225], s[22:23], 0, v[128:129]
	s_add_i32 m0, s57, 0x2000
	s_nop 0
	global_load_lds_dwordx4 v[224:225], off
	v_lshl_add_u64 v[224:225], s[24:25], 0, v[138:139]
	s_mov_b32 m0, s35
	s_nop 0
	global_load_lds_dwordx4 v[224:225], off
	s_mov_b32 m0, s36
	s_nop 0
	global_load_lds_dwordx4 v[226:227], off
	s_waitcnt vmcnt(8)
	s_waitcnt lgkmcnt(0)
	s_barrier
; #define PG8_STAGE(bufoff, gbase, voff) do { _Pragma("unroll") for (int _i = 0; _i < 2; ++_i) \
;         __builtin_amdgcn_global_load_lds((const unsigned*)((const char*)(gbase) + (voff)[_i]), (LAS unsigned*)(lds + (bufoff) + ldsw + _i * 8192), 16, 0, 0); } while (0)
; #define PG8_LDA(dst, b, h) do { _Pragma("unroll") for (int m = 0; m < 4; ++m) _Pragma("unroll") for (int k = 0; k < 2; ++k) dst[m][k] = *(const LAS bf16x8*)(lds + PG8_SA(b, h) + aoff + m * 2048 + k * 1024); } while (0)
; #define PG8_LDB(dst, b, h) do { _Pragma("unroll") for (int n = 0; n < 2; ++n) _Pragma("unroll") for (int k = 0; k < 2; ++k) dst[n][k] = *(const LAS bf16x8*)(lds + PG8_SB(b, h) + boff + n * 2048 + k * 1024); } while (0)
; #define PG8_MMA(ai, bj, At, Bt) do { __builtin_amdgcn_s_setprio(1); _Pragma("unroll") for (int m = 0; m < 4; ++m) _Pragma("unroll") for (int n = 0; n < 2; ++n) _Pragma("unroll") for (int k = 0; k < 2; ++k) \
;         acc[ai][bj][m][n] = __builtin_amdgcn_mfma_f32_16x16x32_bf16(Bt[n][k], At[m][k], acc[ai][bj][m][n], 0, 0, 0); __builtin_amdgcn_s_setprio(0); } while (0)
; #define PG8_WAIT_V(n) asm volatile("s_waitcnt vmcnt(" #n ")" ::: "memory")
; #define PG8_WAIT_L(n) asm volatile("s_waitcnt lgkmcnt(" #n ")" ::: "memory")
; #define PG8_BAR __builtin_amdgcn_s_barrier()
; #define PG8_SCHED __builtin_amdgcn_sched_barrier(0)
; template <class Epi, class Sched>
; __device__ __forceinline__ void gemm_phase(LAS unsigned char* lds, const Sched& S, const Epi& E, bool natural = false) {
;     ...
;             PG8_WAIT_V(8); PG8_WAIT_L(0); PG8_BAR; PG8_MMA(1, 0, At, B0); PG8_MMA(1, 1, At, B1); PG8_BAR; PG8_SCHED;
;             PG8_LDB(B0, 1, 0); PG8_LDB(B1, 1, 1); PG8_SCHED; PG8_LDA(At, 1, 0); PG8_STAGE(PG8_SA(0, 1), a2 + hstep, voffA);
;             PG8_WAIT_V(8); PG8_WAIT_L(0); PG8_BAR; PG8_MMA(0, 0, At, B0); PG8_MMA(0, 1, At, B1); PG8_BAR; PG8_SCHED;
	s_setprio 1
	s_waitcnt lgkmcnt(0)
	v_mfma_f32_16x16x32_bf16 v[60:63], v[150:153], v[188:191], 0
	v_mfma_f32_16x16x32_bf16 v[56:59], v[164:167], v[188:191], 0
	v_mfma_f32_16x16x32_bf16 v[52:55], v[150:153], v[196:199], 0
	v_mfma_f32_16x16x32_bf16 v[48:51], v[164:167], v[196:199], 0
	v_mfma_f32_16x16x32_bf16 v[44:47], v[150:153], v[204:207], 0
	v_mfma_f32_16x16x32_bf16 v[32:35], v[164:167], v[204:207], 0
	v_mfma_f32_16x16x32_bf16 v[20:23], v[150:153], v[212:215], 0
	v_mfma_f32_16x16x32_bf16 v[8:11], v[164:167], v[212:215], 0
	v_mfma_f32_16x16x32_bf16 v[60:63], v[160:163], v[192:195], v[60:63]
	v_mfma_f32_16x16x32_bf16 v[56:59], v[168:171], v[192:195], v[56:59]
	v_mfma_f32_16x16x32_bf16 v[52:55], v[160:163], v[200:203], v[52:55]
	v_mfma_f32_16x16x32_bf16 v[48:51], v[168:171], v[200:203], v[48:51]
	v_mfma_f32_16x16x32_bf16 v[44:47], v[160:163], v[208:211], v[44:47]
	v_mfma_f32_16x16x32_bf16 v[32:35], v[168:171], v[208:211], v[32:35]
	v_mfma_f32_16x16x32_bf16 v[20:23], v[160:163], v[216:219], v[20:23]
	v_mfma_f32_16x16x32_bf16 v[8:11], v[168:171], v[216:219], v[8:11]
	s_setprio 0
	s_setprio 1
	v_mfma_f32_16x16x32_bf16 v[40:43], v[172:175], v[188:191], 0
	v_mfma_f32_16x16x32_bf16 v[36:39], v[180:183], v[188:191], 0
	v_mfma_f32_16x16x32_bf16 v[28:31], v[172:175], v[196:199], 0
	v_mfma_f32_16x16x32_bf16 v[24:27], v[180:183], v[196:199], 0
	v_mfma_f32_16x16x32_bf16 v[16:19], v[172:175], v[204:207], 0
	v_mfma_f32_16x16x32_bf16 v[12:15], v[180:183], v[204:207], 0
	v_mfma_f32_16x16x32_bf16 v[4:7], v[172:175], v[212:215], 0
	v_mfma_f32_16x16x32_bf16 v[0:3], v[180:183], v[212:215], 0
	v_mfma_f32_16x16x32_bf16 v[40:43], v[176:179], v[192:195], v[40:43]
	v_mfma_f32_16x16x32_bf16 v[36:39], v[184:187], v[192:195], v[36:39]
	v_mfma_f32_16x16x32_bf16 v[28:31], v[176:179], v[200:203], v[28:31]
	v_mfma_f32_16x16x32_bf16 v[24:27], v[184:187], v[200:203], v[24:27]
	v_mfma_f32_16x16x32_bf16 v[16:19], v[176:179], v[208:211], v[16:19]
	v_mfma_f32_16x16x32_bf16 v[12:15], v[184:187], v[208:211], v[12:15]
	v_mfma_f32_16x16x32_bf16 v[4:7], v[176:179], v[216:219], v[4:7]
	v_mfma_f32_16x16x32_bf16 v[0:3], v[184:187], v[216:219], v[0:3]
	s_setprio 0
	s_barrier
	s_add_i32 s57, 0, 0x18000
	v_add_u32_e32 v140, s57, v154
	s_add_i32 s58, 0, 0x1c000
	ds_read_b128 v[150:153], v140
	ds_read_b128 v[160:163], v140 offset:1024
	ds_read_b128 v[164:167], v140 offset:2048
	ds_read_b128 v[168:171], v140 offset:3072
	v_add_u32_e32 v140, s58, v154
	ds_read_b128 v[172:175], v140
	ds_read_b128 v[176:179], v140 offset:1024
	ds_read_b128 v[180:183], v140 offset:2048
	ds_read_b128 v[184:187], v140 offset:3072
	s_add_u32 s24, s24, 0x40000
	s_addc_u32 s25, s25, 0
	s_mov_b32 m0, s37
	v_lshl_add_u64 v[228:229], s[24:25], 0, v[138:139]
	ds_read_b128 v[188:191], v158 offset:32768
	ds_read_b128 v[192:195], v158 offset:33792
	ds_read_b128 v[196:199], v158 offset:34816
	ds_read_b128 v[200:203], v158 offset:35840
	ds_read_b128 v[204:207], v158 offset:36864
	ds_read_b128 v[208:211], v158 offset:37888
	ds_read_b128 v[212:215], v158 offset:38912
	ds_read_b128 v[216:219], v158 offset:39936
	global_load_lds_dwordx4 v[228:229], off
	v_lshl_add_u64 v[228:229], s[24:25], 0, v[132:133]
	s_mov_b32 m0, s38
	s_nop 0
	global_load_lds_dwordx4 v[228:229], off
	s_waitcnt vmcnt(8)
	s_waitcnt lgkmcnt(0)
	s_barrier
	s_setprio 1
	s_waitcnt lgkmcnt(0)
	v_mfma_f32_16x16x32_bf16 v[124:127], v[150:153], v[188:191], v[124:127]
	v_mfma_f32_16x16x32_bf16 v[120:123], v[164:167], v[188:191], v[120:123]
	v_mfma_f32_16x16x32_bf16 v[116:119], v[150:153], v[196:199], v[116:119]
	v_mfma_f32_16x16x32_bf16 v[112:115], v[164:167], v[196:199], v[112:115]
	v_mfma_f32_16x16x32_bf16 v[104:107], v[150:153], v[204:207], v[104:107]
	v_mfma_f32_16x16x32_bf16 v[96:99], v[164:167], v[204:207], v[96:99]
	v_mfma_f32_16x16x32_bf16 v[88:91], v[150:153], v[212:215], v[88:91]
	v_mfma_f32_16x16x32_bf16 v[80:83], v[164:167], v[212:215], v[80:83]
	v_mfma_f32_16x16x32_bf16 v[124:127], v[160:163], v[192:195], v[124:127]
	v_mfma_f32_16x16x32_bf16 v[120:123], v[168:171], v[192:195], v[120:123]
	v_mfma_f32_16x16x32_bf16 v[116:119], v[160:163], v[200:203], v[116:119]
	v_mfma_f32_16x16x32_bf16 v[112:115], v[168:171], v[200:203], v[112:115]
	v_mfma_f32_16x16x32_bf16 v[104:107], v[160:163], v[208:211], v[104:107]
	v_mfma_f32_16x16x32_bf16 v[96:99], v[168:171], v[208:211], v[96:99]
	v_mfma_f32_16x16x32_bf16 v[88:91], v[160:163], v[216:219], v[88:91]
	v_mfma_f32_16x16x32_bf16 v[80:83], v[168:171], v[216:219], v[80:83]
	s_setprio 0
	s_setprio 1
	v_mfma_f32_16x16x32_bf16 v[108:111], v[172:175], v[188:191], v[108:111]
	v_mfma_f32_16x16x32_bf16 v[100:103], v[180:183], v[188:191], v[100:103]
	v_mfma_f32_16x16x32_bf16 v[92:95], v[172:175], v[196:199], v[92:95]
	v_mfma_f32_16x16x32_bf16 v[84:87], v[180:183], v[196:199], v[84:87]
	v_mfma_f32_16x16x32_bf16 v[76:79], v[172:175], v[204:207], v[76:79]
	v_mfma_f32_16x16x32_bf16 v[72:75], v[180:183], v[204:207], v[72:75]
	v_mfma_f32_16x16x32_bf16 v[68:71], v[172:175], v[212:215], v[68:71]
	v_mfma_f32_16x16x32_bf16 v[64:67], v[180:183], v[212:215], v[64:67]
	v_mfma_f32_16x16x32_bf16 v[108:111], v[176:179], v[192:195], v[108:111]
	v_mfma_f32_16x16x32_bf16 v[100:103], v[184:187], v[192:195], v[100:103]
	v_mfma_f32_16x16x32_bf16 v[92:95], v[176:179], v[200:203], v[92:95]
	v_mfma_f32_16x16x32_bf16 v[84:87], v[184:187], v[200:203], v[84:87]
	v_mfma_f32_16x16x32_bf16 v[76:79], v[176:179], v[208:211], v[76:79]
	v_mfma_f32_16x16x32_bf16 v[72:75], v[184:187], v[208:211], v[72:75]
	v_mfma_f32_16x16x32_bf16 v[68:71], v[176:179], v[216:219], v[68:71]
	v_mfma_f32_16x16x32_bf16 v[64:67], v[184:187], v[216:219], v[64:67]
	s_setprio 0
	s_barrier
; #define PG8_STAGE(bufoff, gbase, voff) do { _Pragma("unroll") for (int _i = 0; _i < 2; ++_i) \
;         __builtin_amdgcn_global_load_lds((const unsigned*)((const char*)(gbase) + (voff)[_i]), (LAS unsigned*)(lds + (bufoff) + ldsw + _i * 8192), 16, 0, 0); } while (0)
; #define PG8_LDA(dst, b, h) do { _Pragma("unroll") for (int m = 0; m < 4; ++m) _Pragma("unroll") for (int k = 0; k < 2; ++k) dst[m][k] = *(const LAS bf16x8*)(lds + PG8_SA(b, h) + aoff + m * 2048 + k * 1024); } while (0)
; #define PG8_MMA(ai, bj, At, Bt) do { __builtin_amdgcn_s_setprio(1); _Pragma("unroll") for (int m = 0; m < 4; ++m) _Pragma("unroll") for (int n = 0; n < 2; ++n) _Pragma("unroll") for (int k = 0; k < 2; ++k) \
;         acc[ai][bj][m][n] = __builtin_amdgcn_mfma_f32_16x16x32_bf16(Bt[n][k], At[m][k], acc[ai][bj][m][n], 0, 0, 0); __builtin_amdgcn_s_setprio(0); } while (0)
; #define PG8_WAIT_V(n) asm volatile("s_waitcnt vmcnt(" #n ")" ::: "memory")
; #define PG8_WAIT_L(n) asm volatile("s_waitcnt lgkmcnt(" #n ")" ::: "memory")
; #define PG8_BAR __builtin_amdgcn_s_barrier()
; #define PG8_SCHED __builtin_amdgcn_sched_barrier(0)
; template <class Epi, class Sched>
; __device__ __forceinline__ void gemm_phase(LAS unsigned char* lds, const Sched& S, const Epi& E, bool natural = false) {
;     ...
;         for (int t = 0; t < nt; t += 2) {
;     ...
;             PG8_LDA(At, 1, 1); PG8_STAGE(PG8_SB(1, 0), b3, voffB0); PG8_STAGE(PG8_SB(1, 1), b3, voffB1); PG8_STAGE(PG8_SA(1, 0), a3, voffA);
;             PG8_WAIT_V(8); PG8_WAIT_L(0); PG8_BAR; PG8_MMA(1, 0, At, B0); PG8_MMA(1, 1, At, B1); PG8_BAR; PG8_SCHED;
	s_add_u32 s22, s22, 0x80
	s_addc_u32 s23, s23, 0
	s_add_i32 s24, s57, s31
	v_lshl_add_u64 v[220:221], v[220:221], 0, s[8:9]
	s_mov_b32 m0, s24
	ds_read_b128 v[188:191], v158 offset:49152
	ds_read_b128 v[192:195], v158 offset:50176
	ds_read_b128 v[196:199], v158 offset:51200
	ds_read_b128 v[200:203], v158 offset:52224
	ds_read_b128 v[204:207], v158 offset:53248
	ds_read_b128 v[208:211], v158 offset:54272
	ds_read_b128 v[212:215], v158 offset:55296
	ds_read_b128 v[216:219], v158 offset:56320
	global_load_lds_dwordx4 v[220:221], off
	v_lshl_add_u64 v[220:221], v[222:223], 0, s[8:9]
	s_add_i32 m0, s24, 0x2000
	s_add_i32 s24, s58, s31
	global_load_lds_dwordx4 v[220:221], off
	v_lshl_add_u64 v[220:221], s[22:23], 0, v[134:135]
	s_mov_b32 m0, s24
	s_nop 0
	global_load_lds_dwordx4 v[220:221], off
	v_lshl_add_u64 v[220:221], s[22:23], 0, v[128:129]
	s_add_i32 m0, s24, 0x2000
	s_nop 0
	global_load_lds_dwordx4 v[220:221], off
	v_lshl_add_u64 v[220:221], v[224:225], 0, s[8:9]
	s_mov_b32 m0, s41
	s_nop 0
	global_load_lds_dwordx4 v[220:221], off
	v_lshl_add_u64 v[220:221], v[226:227], 0, s[8:9]
	s_mov_b32 m0, s42
	s_nop 0
	global_load_lds_dwordx4 v[220:221], off
	s_waitcnt vmcnt(8)
	s_waitcnt lgkmcnt(0)
	s_barrier
	s_setprio 1
	s_waitcnt lgkmcnt(0)
	v_mfma_f32_16x16x32_bf16 v[60:63], v[150:153], v[188:191], v[60:63]
	v_mfma_f32_16x16x32_bf16 v[56:59], v[164:167], v[188:191], v[56:59]
	v_mfma_f32_16x16x32_bf16 v[52:55], v[150:153], v[196:199], v[52:55]
	v_mfma_f32_16x16x32_bf16 v[48:51], v[164:167], v[196:199], v[48:51]
	v_mfma_f32_16x16x32_bf16 v[44:47], v[150:153], v[204:207], v[44:47]
	v_mfma_f32_16x16x32_bf16 v[32:35], v[164:167], v[204:207], v[32:35]
	v_mfma_f32_16x16x32_bf16 v[20:23], v[150:153], v[212:215], v[20:23]
	v_mfma_f32_16x16x32_bf16 v[8:11], v[164:167], v[212:215], v[8:11]
	v_mfma_f32_16x16x32_bf16 v[60:63], v[160:163], v[192:195], v[60:63]
	v_mfma_f32_16x16x32_bf16 v[56:59], v[168:171], v[192:195], v[56:59]
	v_mfma_f32_16x16x32_bf16 v[52:55], v[160:163], v[200:203], v[52:55]
	v_mfma_f32_16x16x32_bf16 v[48:51], v[168:171], v[200:203], v[48:51]
	v_mfma_f32_16x16x32_bf16 v[44:47], v[160:163], v[208:211], v[44:47]
	v_mfma_f32_16x16x32_bf16 v[32:35], v[168:171], v[208:211], v[32:35]
	v_mfma_f32_16x16x32_bf16 v[20:23], v[160:163], v[216:219], v[20:23]
	v_mfma_f32_16x16x32_bf16 v[8:11], v[168:171], v[216:219], v[8:11]
	s_setprio 0
	s_setprio 1
	v_mfma_f32_16x16x32_bf16 v[40:43], v[172:175], v[188:191], v[40:43]
	v_mfma_f32_16x16x32_bf16 v[36:39], v[180:183], v[188:191], v[36:39]
	v_mfma_f32_16x16x32_bf16 v[28:31], v[172:175], v[196:199], v[28:31]
	v_mfma_f32_16x16x32_bf16 v[24:27], v[180:183], v[196:199], v[24:27]
	v_mfma_f32_16x16x32_bf16 v[16:19], v[172:175], v[204:207], v[16:19]
	v_mfma_f32_16x16x32_bf16 v[12:15], v[180:183], v[204:207], v[12:15]
	v_mfma_f32_16x16x32_bf16 v[4:7], v[172:175], v[212:215], v[4:7]
	v_mfma_f32_16x16x32_bf16 v[0:3], v[180:183], v[212:215], v[0:3]
	v_mfma_f32_16x16x32_bf16 v[40:43], v[176:179], v[192:195], v[40:43]
	v_mfma_f32_16x16x32_bf16 v[36:39], v[184:187], v[192:195], v[36:39]
	v_mfma_f32_16x16x32_bf16 v[28:31], v[176:179], v[200:203], v[28:31]
	v_mfma_f32_16x16x32_bf16 v[24:27], v[184:187], v[200:203], v[24:27]
	v_mfma_f32_16x16x32_bf16 v[16:19], v[176:179], v[208:211], v[16:19]
	v_mfma_f32_16x16x32_bf16 v[12:15], v[184:187], v[208:211], v[12:15]
	v_mfma_f32_16x16x32_bf16 v[4:7], v[176:179], v[216:219], v[4:7]
	v_mfma_f32_16x16x32_bf16 v[0:3], v[184:187], v[216:219], v[0:3]
	s_setprio 0
	s_barrier
	s_add_i32 s56, s56, 2
	s_add_u32 s20, s20, 0x100
	s_addc_u32 s21, s21, 0
	s_add_u32 s54, s54, 0x100
	s_addc_u32 s55, s55, 0
	s_cmp_gt_u32 s56, 13
	s_cbranch_scc0 .LBB0_564
	.p2alignl 6, 3212836864
